# gla_out: odd workgroups start half a unit late (desynchronise load bursts)
# baseline (speedup 1.0000x reference)
;     ...
;     for (int u = vb; u < 2048; u += nb) {
;         const int cidx = u >> 2, hh = u & 3, tok0 = cidx * 64;
;         bf16x8 bfr[8], afr[2][8];
; #pragma unroll
;         for (int ks = 0; ks < 8; ++ks) {
;             bfr[ks] = *(const bf16x8*)(ST + (((size_t)(cidx * 4 + hh)) * 256 + 32 * w + li) * 128 + ks * 16 + h * 8);
; #pragma unroll
;             for (int mi = 0; mi < 2; ++mi) afr[mi][ks] = *(const bf16x8*)(GQ + (size_t)(tok0 + mi * 32 + li) * 512 + hh * 128 + ks * 16 + h * 8);
;         }
;         f32x4 gn[4]; u32x2 rr[2][4];
; #pragma unroll
;         for (int g = 0; g < 4; ++g) {
;             const int v0 = hh * 256 + 32 * w + 8 * g + 4 * h;
;             gn[g] = *(const f32x4*)(on + v0);
; #pragma unroll
;             for (int mi = 0; mi < 2; ++mi) rr[mi][g] = *(const u32x2*)(GR + (size_t)(tok0 + mi * 32 + li) * 1024 + v0);
.LBB0_494:
	s_andn2_b64 vcc, exec, s[0:1]
	s_cbranch_vccnz .LBB0_569
	v_mov_b32_e32 v0, v249
	v_readlane_b32 s0, v253, 0
	s_cmpk_gt_i32 s0, 0x7ff
	s_cbranch_scc1 .LBB0_502
	s_bitcmp1_b32 s0, 0
	s_cbranch_scc0 .Lglaout_nodelay
	s_sleep 127
	s_sleep 60
.Lglaout_nodelay:
	s_lshl_b32 s28, s46, 10
	s_lshl_b64 s[8:9], s[28:29], 2
	v_readlane_b32 s18, v255, 16
	v_and_b32_e32 v78, 31, v0
	v_readlane_b32 s19, v255, 17
	s_add_u32 s8, s18, s8
	s_waitcnt lgkmcnt(0)
	v_ashrrev_i32_e32 v1, 1, v0
	s_addc_u32 s9, s19, s9
	v_lshl_add_u32 v79, v78, 3, 16
	v_bfe_u32 v2, v0, 5, 1
	v_and_b32_e32 v3, 0xffffffe0, v1
	v_readlane_b32 s18, v253, 9
	v_and_b32_e32 v0, 0x1fffffc0, v0
	v_ashrrev_i32_e32 v1, 31, v3
	v_lshlrev_b32_e32 v176, 4, v2
	v_readlane_b32 s19, v253, 10
	v_and_b32_e32 v5, 64, v213
	v_lshl_add_u32 v82, v0, 3, v79
	s_ashr_i32 s1, s0, 31
	v_or_b32_e32 v0, v3, v78
	v_lshl_add_u64 v[48:49], s[18:19], 0, v[176:177]
	v_xor_b32_e32 v4, 32, v213
	v_add_u32_e32 v5, 64, v5
	s_lshl_b64 s[18:19], s[0:1], 16
	v_lshlrev_b64 v[0:1], 8, v[0:1]
	v_cmp_lt_i32_e32 vcc, v4, v5
	v_lshl_add_u64 v[0:1], s[18:19], 0, v[0:1]
	v_readlane_b32 s18, v254, 52
	v_cndmask_b32_e32 v4, v213, v4, vcc
	v_or_b32_e32 v0, v0, v176
	v_readlane_b32 s19, v254, 53
	v_lshl_or_b32 v80, v2, 2, v3
	v_lshlrev_b32_e32 v81, 2, v4
	v_cmp_eq_u32_e32 vcc, 0, v2
	s_lshl_b32 s20, s0, 4
	v_lshl_add_u64 v[50:51], s[18:19], 0, v[0:1]
	s_branch .LBB0_498
